# SGU epilogue: 4 b_s loads hoisted before the MFMA loop, 3 serialized vmcnt(0) round trips per group removed (on top of attention DMA spread)
# speedup vs baseline: 1.0063x; 1.0063x over previous
; #define LAS __attribute__((address_space(3)))
; __device__ __forceinline__ unsigned f2bf(float f) { unsigned u = __builtin_bit_cast(unsigned, f); return (u + 0x7fffu + ((u >> 16) & 1u)) >> 16; }
; __device__ __forceinline__ float bflo(unsigned w) { return __uint_as_float(w << 16); }
; __device__ __forceinline__ float bfhi(unsigned w) { return __uint_as_float(w & 0xffff0000u); }
; __device__ __forceinline__ void sgu_phase(LAS unsigned char* lds, bf16* Z, const float* stats, const bf16* wsb, const float* lng, const float* lnb, const float* bs, int G, int c) {
;     ...
;         for (int g = 0; g < 8; ++g) {
;             GB[tid] = tid < 256 ? lng[g * 256 + tid] : lnb[g * 256 + tid - 256];
;             __syncthreads();
; #pragma unroll
;             for (int j = 0; j < 4; ++j) { const int p = tid + 512 * j, t = p >> 4, pc = p & 15; *(LAS v4u*)(WL + t * 136 + pc * 8) = *(const v4u*)(wsb + (size_t)g * 16384 + t * 128 + pc * 8); }
; #pragma unroll
;             for (int j = 0; j < 8; ++j) { const int s = tid & 127, cc = (tid >> 7) * 8 + 32 * j; const v4u raw = vraw[j];
;                 const float mean = MR[2 * s], rstd = MR[2 * s + 1];
;                 const f32x4 g0 = *(const LAS f32x4*)(GB + cc), g1 = *(const LAS f32x4*)(GB + cc + 4), b0 = *(const LAS f32x4*)(GB + 256 + cc), b1 = *(const LAS f32x4*)(GB + 256 + cc + 4);
;                 LAS bf16* d = VT + cc * 136 + s;
;                 d[0 * 136] = (bf16)f2bf((bflo(raw.x) - mean) * rstd * g0[0] + b0[0]); d[1 * 136] = (bf16)f2bf((bfhi(raw.x) - mean) * rstd * g0[1] + b0[1]);
;                 d[2 * 136] = (bf16)f2bf((bflo(raw.y) - mean) * rstd * g0[2] + b0[2]); d[3 * 136] = (bf16)f2bf((bfhi(raw.y) - mean) * rstd * g0[3] + b0[3]);
;                 d[4 * 136] = (bf16)f2bf((bflo(raw.z) - mean) * rstd * g1[0] + b1[0]); d[5 * 136] = (bf16)f2bf((bfhi(raw.z) - mean) * rstd * g1[1] + b1[1]);
;                 d[6 * 136] = (bf16)f2bf((bflo(raw.w) - mean) * rstd * g1[2] + b1[2]); d[7 * 136] = (bf16)f2bf((bfhi(raw.w) - mean) * rstd * g1[3] + b1[3]); }
.LBB0_271:
	v_lshl_add_u32 v32, s58, 8, v162
	v_ashrrev_i32_e32 v33, 31, v32
	v_lshl_add_u64 v[34:35], v[32:33], 2, s[12:13]
	v_mov_b32_e32 v33, v213
	s_movk_i32 s2, 0xfc00
	v_lshl_add_u64 v[32:33], v[32:33], 2, s[54:55]
	s_mov_b32 s3, -1
	v_lshl_add_u64 v[32:33], v[32:33], 0, s[2:3]
	v_cndmask_b32_e64 v33, v33, v35, s[8:9]
	v_cndmask_b32_e64 v32, v32, v34, s[8:9]
	global_load_dword v38, v[32:33], off
	s_lshl_b32 s18, s58, 15
	v_lshl_add_u64 v[32:33], v[100:101], 0, s[18:19]
	v_lshl_add_u64 v[34:35], v[104:105], 1, v[32:33]
	v_lshl_add_u64 v[36:37], v[106:107], 1, v[32:33]
	v_lshl_add_u64 v[40:41], v[108:109], 1, v[32:33]
	v_lshl_add_u64 v[44:45], v[110:111], 1, v[32:33]
	s_waitcnt vmcnt(8)
	v_lshlrev_b32_e32 v48, 16, v0
	v_and_b32_e32 v49, 0xffff0000, v0
	v_lshlrev_b32_e32 v50, 16, v1
	v_and_b32_e32 v51, 0xffff0000, v1
	v_lshlrev_b32_e32 v56, 16, v2
	v_and_b32_e32 v57, 0xffff0000, v2
	v_lshlrev_b32_e32 v58, 16, v3
	v_and_b32_e32 v59, 0xffff0000, v3
	s_waitcnt vmcnt(7)
	v_lshlrev_b32_e32 v60, 16, v4
	v_and_b32_e32 v61, 0xffff0000, v4
	v_lshlrev_b32_e32 v62, 16, v5
	v_and_b32_e32 v63, 0xffff0000, v5
	v_lshlrev_b32_e32 v64, 16, v6
	v_and_b32_e32 v65, 0xffff0000, v6
	v_lshlrev_b32_e32 v66, 16, v7
	v_and_b32_e32 v67, 0xffff0000, v7
	s_waitcnt vmcnt(6)
	v_lshlrev_b32_e32 v68, 16, v8
	v_lshlrev_b32_e32 v70, 16, v9
	v_lshlrev_b32_e32 v72, 16, v10
	v_and_b32_e32 v69, 0xffff0000, v8
	v_and_b32_e32 v71, 0xffff0000, v9
	v_and_b32_e32 v73, 0xffff0000, v10
	s_mov_b32 s59, s19
	s_lshl_b64 s[2:3], s[58:59], 16
	v_lshl_add_u64 v[130:131], v[124:125], 0, s[2:3]
	s_movk_i32 s2, 0x2000
	s_cmp_eq_u32 s58, 7
	s_waitcnt vmcnt(0)
	ds_write_b32 v165, v38
	s_waitcnt lgkmcnt(0)
	s_barrier
	global_load_dwordx4 v[32:35], v[34:35], off
	s_nop 0
	global_load_dwordx4 v[36:39], v[36:37], off
	s_nop 0
	global_load_dwordx4 v[40:43], v[40:41], off
	s_nop 0
	global_load_dwordx4 v[44:47], v[44:45], off
	s_waitcnt vmcnt(3)
	ds_write_b128 v187, v[32:35]
	s_waitcnt vmcnt(2)
	ds_write_b128 v188, v[36:39]
	s_waitcnt vmcnt(1)
	ds_write_b128 v189, v[40:43]
	s_waitcnt vmcnt(0)
	ds_write_b128 v190, v[44:47]
	ds_read_b64 v[40:41], v191
	ds_read_b128 v[32:35], v168
	ds_read_b128 v[36:39], v168 offset:16
	ds_read_b128 v[42:45], v169
	ds_read_b128 v[52:55], v169 offset:16
	s_waitcnt lgkmcnt(4)
	v_sub_f32_e32 v46, v48, v40
	v_sub_f32_e32 v47, v49, v40
	v_sub_f32_e32 v48, v50, v40
	v_sub_f32_e32 v49, v51, v40
	v_sub_f32_e32 v50, v56, v40
	v_sub_f32_e32 v51, v57, v40
	v_sub_f32_e32 v56, v58, v40
	v_sub_f32_e32 v57, v59, v40
	v_mul_f32_e32 v46, v41, v46
	v_mul_f32_e32 v47, v41, v47
	v_mul_f32_e32 v48, v41, v48
	v_mul_f32_e32 v49, v41, v49
	v_mul_f32_e32 v50, v41, v50
	v_mul_f32_e32 v51, v41, v51
	v_mul_f32_e32 v56, v41, v56
	v_mul_f32_e32 v57, v41, v57
	s_waitcnt lgkmcnt(1)
	v_fma_f32 v32, v46, v32, v42
	v_fma_f32 v33, v47, v33, v43
	v_fma_f32 v34, v48, v34, v44
	v_fmac_f32_e32 v45, v49, v35
	s_waitcnt lgkmcnt(0)
	v_fma_f32 v35, v50, v36, v52
	v_fma_f32 v36, v51, v37, v53
	v_fma_f32 v37, v56, v38, v54
	v_fmac_f32_e32 v55, v57, v39
	v_bfe_u32 v38, v32, 16, 1
	v_bfe_u32 v39, v33, 16, 1
	v_bfe_u32 v42, v34, 16, 1
	v_bfe_u32 v43, v45, 16, 1
	v_bfe_u32 v44, v35, 16, 1
	v_bfe_u32 v46, v36, 16, 1
	v_bfe_u32 v47, v37, 16, 1
	v_bfe_u32 v48, v55, 16, 1
	v_add3_u32 v32, v32, v38, s53
	v_add3_u32 v33, v33, v39, s53
	v_add3_u32 v34, v34, v42, s53
	v_add3_u32 v38, v45, v43, s53
	v_add3_u32 v35, v35, v44, s53
	v_add3_u32 v36, v36, v46, s53
	v_add3_u32 v37, v37, v47, s53
	v_add3_u32 v39, v55, v48, s53
	ds_write_b16_d16_hi v192, v32
	ds_write_b16_d16_hi v192, v33 offset:272
	ds_write_b16_d16_hi v192, v34 offset:544
	ds_write_b16_d16_hi v192, v38 offset:816
	ds_write_b16_d16_hi v192, v35 offset:1088
	ds_write_b16_d16_hi v192, v36 offset:1360
	ds_write_b16_d16_hi v192, v37 offset:1632
	ds_write_b16_d16_hi v192, v39 offset:1904
	ds_read_b128 v[32:35], v170
	ds_read_b128 v[36:39], v171
	ds_read_b128 v[42:45], v170 offset:16
	ds_read_b128 v[46:49], v171 offset:16
	v_sub_f32_e32 v58, v60, v40
	v_sub_f32_e32 v59, v61, v40
	v_sub_f32_e32 v60, v62, v40
	v_sub_f32_e32 v61, v63, v40
	v_sub_f32_e32 v62, v64, v40
	v_sub_f32_e32 v63, v65, v40
	v_sub_f32_e32 v64, v66, v40
	v_sub_f32_e32 v65, v67, v40
	v_mul_f32_e32 v58, v41, v58
	v_mul_f32_e32 v59, v41, v59
	v_mul_f32_e32 v60, v41, v60
	v_mul_f32_e32 v61, v41, v61
	v_mul_f32_e32 v62, v41, v62
	v_mul_f32_e32 v63, v41, v63
	v_mul_f32_e32 v64, v41, v64
	v_mul_f32_e32 v65, v41, v65
	s_waitcnt lgkmcnt(2)
	v_fma_f32 v32, v58, v32, v36
	v_fma_f32 v33, v59, v33, v37
	v_fma_f32 v34, v60, v34, v38
	v_fmac_f32_e32 v39, v61, v35
	s_waitcnt lgkmcnt(0)
	v_fma_f32 v35, v62, v42, v46
	v_fma_f32 v36, v63, v43, v47
	v_fma_f32 v37, v64, v44, v48
	v_fmac_f32_e32 v49, v65, v45
	v_bfe_u32 v38, v32, 16, 1
	v_bfe_u32 v42, v33, 16, 1
	v_bfe_u32 v43, v34, 16, 1
	v_bfe_u32 v44, v39, 16, 1
	v_bfe_u32 v45, v35, 16, 1
	v_bfe_u32 v46, v36, 16, 1
	v_bfe_u32 v47, v37, 16, 1
	v_bfe_u32 v48, v49, 16, 1
	v_add3_u32 v32, v32, v38, s53
	v_add3_u32 v33, v33, v42, s53
	v_add3_u32 v34, v34, v43, s53
	v_add3_u32 v38, v39, v44, s53
	v_add3_u32 v35, v35, v45, s53
	v_add3_u32 v36, v36, v46, s53
	v_add3_u32 v37, v37, v47, s53
	v_add3_u32 v39, v49, v48, s53
	ds_write_b16_d16_hi v192, v32 offset:8704
	ds_write_b16_d16_hi v192, v33 offset:8976
	ds_write_b16_d16_hi v192, v34 offset:9248
	ds_write_b16_d16_hi v192, v38 offset:9520
	ds_write_b16_d16_hi v192, v35 offset:9792
	ds_write_b16_d16_hi v192, v36 offset:10064
	ds_write_b16_d16_hi v192, v37 offset:10336
	ds_write_b16_d16_hi v192, v39 offset:10608
	ds_read_b128 v[42:45], v172
	ds_read_b128 v[46:49], v173
	ds_read_b128 v[36:39], v172 offset:16
	ds_read_b128 v[32:35], v173 offset:16
	v_sub_f32_e32 v66, v68, v40
	v_sub_f32_e32 v68, v70, v40
	v_sub_f32_e32 v70, v72, v40
	v_sub_f32_e32 v67, v69, v40
	v_sub_f32_e32 v69, v71, v40
	v_sub_f32_e32 v71, v73, v40
	v_mul_f32_e32 v66, v41, v66
	v_mul_f32_e32 v52, v41, v70
	v_mul_f32_e32 v67, v41, v67
	v_mul_f32_e32 v50, v41, v68
	v_mul_f32_e32 v51, v41, v69
	v_mul_f32_e32 v53, v41, v71
	s_waitcnt lgkmcnt(2)
; #define LAS __attribute__((address_space(3)))
; __device__ __forceinline__ unsigned f2bf(float f) { unsigned u = __builtin_bit_cast(unsigned, f); return (u + 0x7fffu + ((u >> 16) & 1u)) >> 16; }
; __device__ __forceinline__ float bflo(unsigned w) { return __uint_as_float(w << 16); }
; __device__ __forceinline__ float bfhi(unsigned w) { return __uint_as_float(w & 0xffff0000u); }
; __device__ __forceinline__ void sgu_phase(LAS unsigned char* lds, bf16* Z, const float* stats, const bf16* wsb, const float* lng, const float* lnb, const float* bs, int G, int c) {
;     ...
;             for (int j = 0; j < 8; ++j) { const int s = tid & 127, cc = (tid >> 7) * 8 + 32 * j; const v4u raw = vraw[j];
;                 const float mean = MR[2 * s], rstd = MR[2 * s + 1];
;                 const f32x4 g0 = *(const LAS f32x4*)(GB + cc), g1 = *(const LAS f32x4*)(GB + cc + 4), b0 = *(const LAS f32x4*)(GB + 256 + cc), b1 = *(const LAS f32x4*)(GB + 256 + cc + 4);
;                 LAS bf16* d = VT + cc * 136 + s;
;                 d[0 * 136] = (bf16)f2bf((bflo(raw.x) - mean) * rstd * g0[0] + b0[0]); d[1 * 136] = (bf16)f2bf((bfhi(raw.x) - mean) * rstd * g0[1] + b0[1]);
;                 d[2 * 136] = (bf16)f2bf((bflo(raw.y) - mean) * rstd * g0[2] + b0[2]); d[3 * 136] = (bf16)f2bf((bfhi(raw.y) - mean) * rstd * g0[3] + b0[3]);
;                 d[4 * 136] = (bf16)f2bf((bflo(raw.z) - mean) * rstd * g1[0] + b1[0]); d[5 * 136] = (bf16)f2bf((bfhi(raw.z) - mean) * rstd * g1[1] + b1[1]);
;                 d[6 * 136] = (bf16)f2bf((bflo(raw.w) - mean) * rstd * g1[2] + b1[2]); d[7 * 136] = (bf16)f2bf((bfhi(raw.w) - mean) * rstd * g1[3] + b1[3]); }
	v_fma_f32 v42, v66, v42, v46
	s_waitcnt lgkmcnt(0)
	v_fma_f32 v32, v52, v36, v32
	v_fma_f32 v43, v67, v43, v47
	v_fma_f32 v44, v50, v44, v48
	v_fmac_f32_e32 v49, v51, v45
	v_fma_f32 v33, v53, v37, v33
	v_bfe_u32 v36, v42, 16, 1
	v_bfe_u32 v47, v32, 16, 1
	v_bfe_u32 v37, v43, 16, 1
	v_bfe_u32 v45, v44, 16, 1
	v_bfe_u32 v46, v49, 16, 1
	v_bfe_u32 v48, v33, 16, 1
	v_add3_u32 v36, v42, v36, s53
	v_add3_u32 v32, v32, v47, s53
	v_add3_u32 v37, v43, v37, s53
	v_add3_u32 v42, v44, v45, s53
	v_add3_u32 v43, v49, v46, s53
	v_add3_u32 v33, v33, v48, s53
	ds_write_b16_d16_hi v192, v36 offset:17408
	ds_write_b16_d16_hi v192, v37 offset:17680
	ds_write_b16_d16_hi v192, v42 offset:17952
	ds_write_b16_d16_hi v192, v43 offset:18224
	ds_write_b16_d16_hi v192, v32 offset:18496
	ds_write_b16_d16_hi v192, v33 offset:18768
	v_lshlrev_b32_e32 v32, 16, v11
	v_sub_f32_e32 v32, v32, v40
	v_mul_f32_e32 v32, v41, v32
	v_fma_f32 v32, v32, v38, v34
	v_bfe_u32 v33, v32, 16, 1
	v_add3_u32 v32, v32, v33, s53
	ds_write_b16_d16_hi v192, v32 offset:19040
	v_and_b32_e32 v32, 0xffff0000, v11
	v_sub_f32_e32 v32, v32, v40
	v_mul_f32_e32 v32, v41, v32
	v_fmac_f32_e32 v35, v32, v39
	v_bfe_u32 v32, v35, 16, 1
	v_add3_u32 v32, v35, v32, s53
	ds_write_b16_d16_hi v192, v32 offset:19312
	ds_read_b128 v[32:35], v174
	ds_read_b128 v[36:39], v174 offset:16
	ds_read_b128 v[42:45], v175
	ds_read_b128 v[46:49], v175 offset:16
	v_lshlrev_b32_e32 v50, 16, v12
	v_sub_f32_e32 v50, v50, v40
	v_mul_f32_e32 v50, v41, v50
	s_waitcnt lgkmcnt(1)
	v_fma_f32 v32, v50, v32, v42
	v_bfe_u32 v42, v32, 16, 1
	v_add3_u32 v32, v32, v42, s53
	ds_write_b16_d16_hi v192, v32 offset:26112
	v_and_b32_e32 v32, 0xffff0000, v12
	v_sub_f32_e32 v32, v32, v40
	v_mul_f32_e32 v32, v41, v32
	v_fma_f32 v32, v32, v33, v43
	v_bfe_u32 v33, v32, 16, 1
	v_add3_u32 v32, v32, v33, s53
	ds_write_b16_d16_hi v192, v32 offset:26384
	v_lshlrev_b32_e32 v32, 16, v13
	v_sub_f32_e32 v32, v32, v40
	v_mul_f32_e32 v32, v41, v32
	v_fma_f32 v32, v32, v34, v44
	v_bfe_u32 v33, v32, 16, 1
	v_add3_u32 v32, v32, v33, s53
	ds_write_b16_d16_hi v192, v32 offset:26656
	v_and_b32_e32 v32, 0xffff0000, v13
	v_sub_f32_e32 v32, v32, v40
	v_mul_f32_e32 v32, v41, v32
	v_fmac_f32_e32 v45, v32, v35
	v_bfe_u32 v32, v45, 16, 1
	v_add3_u32 v32, v45, v32, s53
	ds_write_b16_d16_hi v192, v32 offset:26928
	v_lshlrev_b32_e32 v32, 16, v14
	v_sub_f32_e32 v32, v32, v40
	v_mul_f32_e32 v32, v41, v32
	s_waitcnt lgkmcnt(4)
	v_fma_f32 v32, v32, v36, v46
	v_bfe_u32 v33, v32, 16, 1
	v_add3_u32 v32, v32, v33, s53
	ds_write_b16_d16_hi v192, v32 offset:27200
	v_and_b32_e32 v32, 0xffff0000, v14
	v_sub_f32_e32 v32, v32, v40
	v_mul_f32_e32 v32, v41, v32
	v_fma_f32 v32, v32, v37, v47
	v_bfe_u32 v33, v32, 16, 1
	v_add3_u32 v32, v32, v33, s53
	ds_write_b16_d16_hi v192, v32 offset:27472
	v_lshlrev_b32_e32 v32, 16, v15
	v_sub_f32_e32 v32, v32, v40
	v_mul_f32_e32 v32, v41, v32
	v_fma_f32 v32, v32, v38, v48
	v_bfe_u32 v33, v32, 16, 1
	v_add3_u32 v32, v32, v33, s53
	ds_write_b16_d16_hi v192, v32 offset:27744
	v_and_b32_e32 v32, 0xffff0000, v15
	v_sub_f32_e32 v32, v32, v40
	v_mul_f32_e32 v32, v41, v32
	v_fmac_f32_e32 v49, v32, v39
	v_bfe_u32 v32, v49, 16, 1
	v_add3_u32 v32, v49, v32, s53
	ds_write_b16_d16_hi v192, v32 offset:28016
	ds_read_b128 v[32:35], v176
	ds_read_b128 v[36:39], v176 offset:16
	ds_read_b128 v[42:45], v177
	ds_read_b128 v[46:49], v177 offset:16
	v_lshlrev_b32_e32 v50, 16, v16
	v_sub_f32_e32 v50, v50, v40
	v_mul_f32_e32 v50, v41, v50
	s_waitcnt lgkmcnt(1)
	v_fma_f32 v32, v50, v32, v42
	v_bfe_u32 v42, v32, 16, 1
	v_add3_u32 v32, v32, v42, s53
	ds_write_b16_d16_hi v192, v32 offset:34816
	v_and_b32_e32 v32, 0xffff0000, v16
	v_sub_f32_e32 v32, v32, v40
	v_mul_f32_e32 v32, v41, v32
	v_fma_f32 v32, v32, v33, v43
	v_bfe_u32 v33, v32, 16, 1
	v_add3_u32 v32, v32, v33, s53
	ds_write_b16_d16_hi v192, v32 offset:35088
	v_lshlrev_b32_e32 v32, 16, v17
	v_sub_f32_e32 v32, v32, v40
	v_mul_f32_e32 v32, v41, v32
	v_fma_f32 v32, v32, v34, v44
	v_bfe_u32 v33, v32, 16, 1
	v_add3_u32 v32, v32, v33, s53
	ds_write_b16_d16_hi v192, v32 offset:35360
	v_and_b32_e32 v32, 0xffff0000, v17
	v_sub_f32_e32 v32, v32, v40
	v_mul_f32_e32 v32, v41, v32
	v_fmac_f32_e32 v45, v32, v35
	v_bfe_u32 v32, v45, 16, 1
	v_add3_u32 v32, v45, v32, s53
	ds_write_b16_d16_hi v192, v32 offset:35632
	v_lshlrev_b32_e32 v32, 16, v18
	v_sub_f32_e32 v32, v32, v40
	v_mul_f32_e32 v32, v41, v32
	s_waitcnt lgkmcnt(4)
	v_fma_f32 v32, v32, v36, v46
	v_bfe_u32 v33, v32, 16, 1
	v_add3_u32 v32, v32, v33, s53
	ds_write_b16_d16_hi v192, v32 offset:35904
	v_and_b32_e32 v32, 0xffff0000, v18
	v_sub_f32_e32 v32, v32, v40
	v_mul_f32_e32 v32, v41, v32
	v_fma_f32 v32, v32, v37, v47
	v_bfe_u32 v33, v32, 16, 1
	v_add3_u32 v32, v32, v33, s53
	ds_write_b16_d16_hi v192, v32 offset:36176
	v_lshlrev_b32_e32 v32, 16, v19
	v_sub_f32_e32 v32, v32, v40
	v_mul_f32_e32 v32, v41, v32
	v_fma_f32 v32, v32, v38, v48
	v_bfe_u32 v33, v32, 16, 1
	v_add3_u32 v32, v32, v33, s53
	ds_write_b16_d16_hi v192, v32 offset:36448
	v_and_b32_e32 v32, 0xffff0000, v19
	v_sub_f32_e32 v32, v32, v40
	v_mul_f32_e32 v32, v41, v32
	v_fmac_f32_e32 v49, v32, v39
	v_bfe_u32 v32, v49, 16, 1
	v_add3_u32 v32, v49, v32, s53
	ds_write_b16_d16_hi v192, v32 offset:36720
	ds_read_b128 v[32:35], v178
	ds_read_b128 v[36:39], v178 offset:16
	ds_read_b128 v[42:45], v179
	ds_read_b128 v[46:49], v179 offset:16
	v_lshlrev_b32_e32 v50, 16, v20
	v_sub_f32_e32 v50, v50, v40
	v_mul_f32_e32 v50, v41, v50
	s_waitcnt lgkmcnt(1)
; #define LAS __attribute__((address_space(3)))
; __device__ __forceinline__ unsigned f2bf(float f) { unsigned u = __builtin_bit_cast(unsigned, f); return (u + 0x7fffu + ((u >> 16) & 1u)) >> 16; }
; __device__ __forceinline__ float bflo(unsigned w) { return __uint_as_float(w << 16); }
; __device__ __forceinline__ float bfhi(unsigned w) { return __uint_as_float(w & 0xffff0000u); }
; __device__ __forceinline__ void sgu_phase(LAS unsigned char* lds, bf16* Z, const float* stats, const bf16* wsb, const float* lng, const float* lnb, const float* bs, int G, int c) {
;     ...
;             for (int j = 0; j < 8; ++j) { const int s = tid & 127, cc = (tid >> 7) * 8 + 32 * j; const v4u raw = vraw[j];
;                 const float mean = MR[2 * s], rstd = MR[2 * s + 1];
;                 const f32x4 g0 = *(const LAS f32x4*)(GB + cc), g1 = *(const LAS f32x4*)(GB + cc + 4), b0 = *(const LAS f32x4*)(GB + 256 + cc), b1 = *(const LAS f32x4*)(GB + 256 + cc + 4);
;                 LAS bf16* d = VT + cc * 136 + s;
;                 d[0 * 136] = (bf16)f2bf((bflo(raw.x) - mean) * rstd * g0[0] + b0[0]); d[1 * 136] = (bf16)f2bf((bfhi(raw.x) - mean) * rstd * g0[1] + b0[1]);
;                 d[2 * 136] = (bf16)f2bf((bflo(raw.y) - mean) * rstd * g0[2] + b0[2]); d[3 * 136] = (bf16)f2bf((bfhi(raw.y) - mean) * rstd * g0[3] + b0[3]);
;                 d[4 * 136] = (bf16)f2bf((bflo(raw.z) - mean) * rstd * g1[0] + b1[0]); d[5 * 136] = (bf16)f2bf((bfhi(raw.z) - mean) * rstd * g1[1] + b1[1]);
;                 d[6 * 136] = (bf16)f2bf((bflo(raw.w) - mean) * rstd * g1[2] + b1[2]); d[7 * 136] = (bf16)f2bf((bfhi(raw.w) - mean) * rstd * g1[3] + b1[3]); }
;             __syncthreads();
;             v2u uu[4][4];
; #pragma unroll
;             for (int m = 0; m < 4; ++m) { const bf16* zr = Z + ((size_t)ck * 8 + g) * 32768 + (64 * wr + 16 * m + fr) * 256 + 64 * wc + 4 * fq;
	v_fma_f32 v32, v50, v32, v42
	v_bfe_u32 v42, v32, 16, 1
	v_add3_u32 v32, v32, v42, s53
	ds_write_b16_d16_hi v192, v32 offset:43520
	v_and_b32_e32 v32, 0xffff0000, v20
	v_sub_f32_e32 v32, v32, v40
	v_mul_f32_e32 v32, v41, v32
	v_fma_f32 v32, v32, v33, v43
	v_bfe_u32 v33, v32, 16, 1
	v_add3_u32 v32, v32, v33, s53
	ds_write_b16_d16_hi v192, v32 offset:43792
	v_lshlrev_b32_e32 v32, 16, v21
	v_sub_f32_e32 v32, v32, v40
	v_mul_f32_e32 v32, v41, v32
	v_fma_f32 v32, v32, v34, v44
	v_bfe_u32 v33, v32, 16, 1
	v_add3_u32 v32, v32, v33, s53
	ds_write_b16_d16_hi v192, v32 offset:44064
	v_and_b32_e32 v32, 0xffff0000, v21
	v_sub_f32_e32 v32, v32, v40
	v_mul_f32_e32 v32, v41, v32
	v_fmac_f32_e32 v45, v32, v35
	v_bfe_u32 v32, v45, 16, 1
	v_add3_u32 v32, v45, v32, s53
	ds_write_b16_d16_hi v192, v32 offset:44336
	v_lshlrev_b32_e32 v32, 16, v22
	v_sub_f32_e32 v32, v32, v40
	v_mul_f32_e32 v32, v41, v32
	s_waitcnt lgkmcnt(4)
	v_fma_f32 v32, v32, v36, v46
	v_bfe_u32 v33, v32, 16, 1
	v_add3_u32 v32, v32, v33, s53
	ds_write_b16_d16_hi v192, v32 offset:44608
	v_and_b32_e32 v32, 0xffff0000, v22
	v_sub_f32_e32 v32, v32, v40
	v_mul_f32_e32 v32, v41, v32
	v_fma_f32 v32, v32, v37, v47
	v_bfe_u32 v33, v32, 16, 1
	v_add3_u32 v32, v32, v33, s53
	ds_write_b16_d16_hi v192, v32 offset:44880
	v_lshlrev_b32_e32 v32, 16, v23
	v_sub_f32_e32 v32, v32, v40
	v_mul_f32_e32 v32, v41, v32
	v_fma_f32 v32, v32, v38, v48
	v_bfe_u32 v33, v32, 16, 1
	v_add3_u32 v32, v32, v33, s53
	ds_write_b16_d16_hi v192, v32 offset:45152
	v_and_b32_e32 v32, 0xffff0000, v23
	v_sub_f32_e32 v32, v32, v40
	v_mul_f32_e32 v32, v41, v32
	v_fmac_f32_e32 v49, v32, v39
	v_bfe_u32 v32, v49, 16, 1
	v_add3_u32 v32, v49, v32, s53
	ds_write_b16_d16_hi v192, v32 offset:45424
	ds_read_b128 v[32:35], v180
	ds_read_b128 v[36:39], v180 offset:16
	ds_read_b128 v[42:45], v181
	ds_read_b128 v[46:49], v181 offset:16
	v_lshlrev_b32_e32 v50, 16, v24
	v_sub_f32_e32 v50, v50, v40
	v_mul_f32_e32 v50, v41, v50
	s_waitcnt lgkmcnt(1)
	v_fma_f32 v32, v50, v32, v42
	v_bfe_u32 v42, v32, 16, 1
	v_add3_u32 v32, v32, v42, s53
	ds_write_b16_d16_hi v192, v32 offset:52224
	v_and_b32_e32 v32, 0xffff0000, v24
	v_sub_f32_e32 v32, v32, v40
	v_mul_f32_e32 v32, v41, v32
	v_fma_f32 v32, v32, v33, v43
	v_bfe_u32 v33, v32, 16, 1
	v_add3_u32 v32, v32, v33, s53
	ds_write_b16_d16_hi v192, v32 offset:52496
	v_lshlrev_b32_e32 v32, 16, v25
	v_sub_f32_e32 v32, v32, v40
	v_mul_f32_e32 v32, v41, v32
	v_fma_f32 v32, v32, v34, v44
	v_bfe_u32 v33, v32, 16, 1
	v_add3_u32 v32, v32, v33, s53
	ds_write_b16_d16_hi v192, v32 offset:52768
	v_and_b32_e32 v32, 0xffff0000, v25
	v_sub_f32_e32 v32, v32, v40
	v_mul_f32_e32 v32, v41, v32
	v_fmac_f32_e32 v45, v32, v35
	v_bfe_u32 v32, v45, 16, 1
	v_add3_u32 v32, v45, v32, s53
	ds_write_b16_d16_hi v192, v32 offset:53040
	v_lshlrev_b32_e32 v32, 16, v26
	v_sub_f32_e32 v32, v32, v40
	v_mul_f32_e32 v32, v41, v32
	s_waitcnt lgkmcnt(4)
	v_fma_f32 v32, v32, v36, v46
	v_bfe_u32 v33, v32, 16, 1
	v_add3_u32 v32, v32, v33, s53
	ds_write_b16_d16_hi v192, v32 offset:53312
	v_and_b32_e32 v32, 0xffff0000, v26
	v_sub_f32_e32 v32, v32, v40
	v_mul_f32_e32 v32, v41, v32
	v_fma_f32 v32, v32, v37, v47
	v_bfe_u32 v33, v32, 16, 1
	v_add3_u32 v32, v32, v33, s53
	ds_write_b16_d16_hi v192, v32 offset:53584
	v_lshlrev_b32_e32 v32, 16, v27
	v_sub_f32_e32 v32, v32, v40
	v_mul_f32_e32 v32, v41, v32
	v_fma_f32 v32, v32, v38, v48
	v_bfe_u32 v33, v32, 16, 1
	v_add3_u32 v32, v32, v33, s53
	ds_write_b16_d16_hi v192, v32 offset:53856
	v_and_b32_e32 v32, 0xffff0000, v27
	v_sub_f32_e32 v32, v32, v40
	v_mul_f32_e32 v32, v41, v32
	v_fmac_f32_e32 v49, v32, v39
	v_bfe_u32 v32, v49, 16, 1
	v_add3_u32 v32, v49, v32, s53
	ds_write_b16_d16_hi v192, v32 offset:54128
	ds_read_b128 v[32:35], v182
	ds_read_b128 v[36:39], v182 offset:16
	ds_read_b128 v[42:45], v183
	ds_read_b128 v[46:49], v183 offset:16
	v_lshlrev_b32_e32 v50, 16, v28
	v_sub_f32_e32 v50, v50, v40
	v_mul_f32_e32 v50, v41, v50
	s_waitcnt lgkmcnt(1)
	v_fma_f32 v32, v50, v32, v42
	v_bfe_u32 v42, v32, 16, 1
	v_add3_u32 v32, v32, v42, s53
	ds_write_b16_d16_hi v192, v32 offset:60928
	v_and_b32_e32 v32, 0xffff0000, v28
	v_sub_f32_e32 v32, v32, v40
	v_mul_f32_e32 v32, v41, v32
	v_fma_f32 v32, v32, v33, v43
	v_bfe_u32 v33, v32, 16, 1
	v_add3_u32 v32, v32, v33, s53
	ds_write_b16_d16_hi v192, v32 offset:61200
	v_lshlrev_b32_e32 v32, 16, v29
	v_sub_f32_e32 v32, v32, v40
	v_mul_f32_e32 v32, v41, v32
	v_fma_f32 v32, v32, v34, v44
	v_bfe_u32 v33, v32, 16, 1
	v_add3_u32 v32, v32, v33, s53
	ds_write_b16_d16_hi v192, v32 offset:61472
	v_and_b32_e32 v32, 0xffff0000, v29
	v_sub_f32_e32 v32, v32, v40
	v_mul_f32_e32 v32, v41, v32
	v_fmac_f32_e32 v45, v32, v35
	v_bfe_u32 v32, v45, 16, 1
	v_add3_u32 v32, v45, v32, s53
	ds_write_b16_d16_hi v192, v32 offset:61744
	v_lshlrev_b32_e32 v32, 16, v30
	v_sub_f32_e32 v32, v32, v40
	v_mul_f32_e32 v32, v41, v32
	s_waitcnt lgkmcnt(4)
	v_fma_f32 v32, v32, v36, v46
	v_bfe_u32 v33, v32, 16, 1
	v_add3_u32 v32, v32, v33, s53
	ds_write_b16_d16_hi v192, v32 offset:62016
	v_and_b32_e32 v32, 0xffff0000, v30
	v_sub_f32_e32 v32, v32, v40
	v_mul_f32_e32 v32, v41, v32
	v_fma_f32 v32, v32, v37, v47
	v_bfe_u32 v33, v32, 16, 1
	v_add3_u32 v32, v32, v33, s53
	ds_write_b16_d16_hi v192, v32 offset:62288
	v_lshlrev_b32_e32 v32, 16, v31
	v_sub_f32_e32 v32, v32, v40
	v_mul_f32_e32 v32, v41, v32
	v_fma_f32 v32, v32, v38, v48
	v_bfe_u32 v33, v32, 16, 1
	v_add3_u32 v32, v32, v33, s53
	ds_write_b16_d16_hi v192, v32 offset:62560
	v_and_b32_e32 v32, 0xffff0000, v31
	v_sub_f32_e32 v32, v32, v40
	v_mul_f32_e32 v32, v41, v32
	v_fmac_f32_e32 v49, v32, v39
	v_bfe_u32 v32, v49, 16, 1
	v_add3_u32 v32, v49, v32, s53
	ds_write_b16_d16_hi v192, v32 offset:62832
	v_lshl_add_u64 v[32:33], v[112:113], 1, v[130:131]
	v_add_co_u32_e32 v34, vcc, s2, v32
	s_movk_i32 s2, 0x4000
	s_nop 0
	v_addc_co_u32_e32 v35, vcc, 0, v33, vcc
	s_waitcnt lgkmcnt(0)
	s_barrier
; #define SGU_LOADVW(g_) do { _Pragma("unroll") for (int j = 0; j < 8; ++j) vraw[j] = *(const v4u*)(vb + (size_t)(g_) * 32768 + j * 32); } while (0)
; __device__ __forceinline__ void sgu_phase(LAS unsigned char* lds, bf16* Z, const float* stats, const bf16* wsb, const float* lng, const float* lnb, const float* bs, int G, int c) {
;     ...
;             v2u uu[4][4];
; #pragma unroll
;             for (int m = 0; m < 4; ++m) { const bf16* zr = Z + ((size_t)ck * 8 + g) * 32768 + (64 * wr + 16 * m + fr) * 256 + 64 * wc + 4 * fq;
; #pragma unroll
;                 for (int n = 0; n < 4; ++n) uu[m][n] = *(const v2u*)(zr + 16 * n); }
;             asm volatile("" ::: "memory");
;             if (g < 7) SGU_LOADVW(g + 1);
	global_load_dwordx2 v[158:159], v[32:33], off
	global_load_dwordx2 v[156:157], v[32:33], off offset:32
	global_load_dwordx2 v[154:155], v[32:33], off offset:64
	global_load_dwordx2 v[152:153], v[32:33], off offset:96
	global_load_dwordx2 v[150:151], v[34:35], off
	global_load_dwordx2 v[148:149], v[34:35], off offset:32
	global_load_dwordx2 v[146:147], v[34:35], off offset:64
	global_load_dwordx2 v[144:145], v[34:35], off offset:96
	v_add_co_u32_e32 v34, vcc, s2, v32
	s_nop 1
	v_addc_co_u32_e32 v35, vcc, 0, v33, vcc
	v_add_co_u32_e32 v32, vcc, 0x6000, v32
	global_load_dwordx2 v[142:143], v[34:35], off
	global_load_dwordx2 v[140:141], v[34:35], off offset:32
	global_load_dwordx2 v[138:139], v[34:35], off offset:64
	global_load_dwordx2 v[136:137], v[34:35], off offset:96
	v_addc_co_u32_e32 v33, vcc, 0, v33, vcc
	global_load_dwordx2 v[134:135], v[32:33], off
	global_load_dwordx2 v[132:133], v[32:33], off offset:32
	global_load_dwordx2 v[128:129], v[32:33], off offset:64
	global_load_dwordx2 v[126:127], v[32:33], off offset:96
	v_lshl_add_u32 v240, s58, 7, v166
	v_ashrrev_i32_e32 v241, 31, v240
	v_lshl_add_u64 v[240:241], v[240:241], 2, s[56:57]
	global_load_dword v222, v[240:241], off
	global_load_dword v223, v[240:241], off offset:64
	global_load_dword v224, v[240:241], off offset:128
	global_load_dword v225, v[240:241], off offset:192
	s_cbranch_scc1 .LBB0_273
	s_lshl_b32 s18, s58, 16
	v_lshl_add_u64 v[0:1], v[122:123], 0, s[18:19]
	v_add_co_u32_e32 v28, vcc, 0x10000, v0
	s_nop 1
	v_addc_co_u32_e32 v29, vcc, 0, v1, vcc
	global_load_dwordx4 v[0:3], v[28:29], off
	global_load_dwordx4 v[4:7], v[28:29], off offset:64
	global_load_dwordx4 v[8:11], v[28:29], off offset:128
	global_load_dwordx4 v[12:15], v[28:29], off offset:192
	global_load_dwordx4 v[16:19], v[28:29], off offset:256
	global_load_dwordx4 v[20:23], v[28:29], off offset:320
	global_load_dwordx4 v[24:27], v[28:29], off offset:384
	s_nop 0
	global_load_dwordx4 v[28:31], v[28:29], off offset:448

; #define LAS __attribute__((address_space(3)))
; __device__ __forceinline__ unsigned pk2(float lo, float hi) { return pg8::cvt_pk_bf16(lo, hi); }
; __device__ __forceinline__ float bflo(unsigned w) { return __uint_as_float(w << 16); }
; __device__ __forceinline__ float bfhi(unsigned w) { return __uint_as_float(w & 0xffff0000u); }
; __device__ __forceinline__ void sgu_phase(LAS unsigned char* lds, bf16* Z, const float* stats, const bf16* wsb, const float* lng, const float* lnb, const float* bs, int G, int c) {
;     ...
;             f32x4 acc[4][4];
; #pragma unroll
;             for (int m = 0; m < 4; ++m)
; #pragma unroll
;                 for (int n = 0; n < 4; ++n) acc[m][n] = (f32x4){0.f, 0.f, 0.f, 0.f};
;             const int kend = wr == 0 ? 2 : 4;
;             for (int ks = 0; ks < kend; ++ks) { bf16x8 af[4], bfr[4];
; #pragma unroll
;                 for (int m = 0; m < 4; ++m) af[m] = *(const LAS bf16x8*)(WL + (64 * wr + 16 * m + fr) * 136 + ks * 32 + fq * 8);
; #pragma unroll
;                 for (int n = 0; n < 4; ++n) bfr[n] = *(const LAS bf16x8*)(VT + (64 * wc + 16 * n + fr) * 136 + ks * 32 + fq * 8);
; #pragma unroll
;                 for (int m = 0; m < 4; ++m)
; #pragma unroll
;                     for (int n = 0; n < 4; ++n) acc[m][n] = __builtin_amdgcn_mfma_f32_16x16x32_bf16(bfr[n], af[m], acc[m][n], 0, 0, 0); }
; #pragma unroll
;             for (int m = 0; m < 4; ++m) { const int t = 64 * wr + 16 * m + fr; const float bsv = bs[g * 128 + t]; bf16* zr = Z + ((size_t)ck * 8 + g) * 32768 + t * 256 + 64 * wc + 4 * fq;
; #pragma unroll
;                 for (int n = 0; n < 4; ++n) { const v2u u2 = uu[m][n]; const f32x4 a = acc[m][n];
;                     *(v2u*)(zr + 16 * n) = (v2u){pk2(bflo(u2.x) * (a[0] + bsv), bfhi(u2.x) * (a[1] + bsv)), pk2(bflo(u2.y) * (a[2] + bsv), bfhi(u2.y) * (a[3] + bsv))}; } }
.LBB0_274:
	v_add_u32_e32 v193, v160, v167
	v_add_u32_e32 v210, v161, v167
	v_add_u32_e32 v202, 0x11000, v193
	v_add_u32_e32 v206, 0x12100, v193
	ds_read_b128 v[194:197], v210
	ds_read_b128 v[198:201], v210 offset:4352
	ds_read_b128 v[202:205], v202
	ds_read_b128 v[206:209], v206
	ds_read_b128 v[214:217], v210 offset:8704
	ds_read_b128 v[218:221], v210 offset:13056
	s_add_i32 s2, s2, -1
	s_waitcnt lgkmcnt(3)
	v_mfma_f32_16x16x32_bf16 v[92:95], v[194:197], v[202:205], v[92:95]
	v_add_u32_e32 v161, 64, v161
	s_cmp_eq_u32 s2, 0
	v_add_u32_e32 v160, 64, v160
	v_mfma_f32_16x16x32_bf16 v[88:91], v[198:201], v[202:205], v[88:91]
	s_waitcnt lgkmcnt(1)
	v_mfma_f32_16x16x32_bf16 v[84:87], v[214:217], v[202:205], v[84:87]
	s_waitcnt lgkmcnt(0)
	v_mfma_f32_16x16x32_bf16 v[80:83], v[218:221], v[202:205], v[80:83]
	v_add_u32_e32 v202, 0x13200, v193
	v_add_u32_e32 v193, 0x14300, v193
	v_mfma_f32_16x16x32_bf16 v[76:79], v[194:197], v[206:209], v[76:79]
	v_mfma_f32_16x16x32_bf16 v[72:75], v[198:201], v[206:209], v[72:75]
	v_mfma_f32_16x16x32_bf16 v[68:71], v[214:217], v[206:209], v[68:71]
	v_mfma_f32_16x16x32_bf16 v[64:67], v[218:221], v[206:209], v[64:67]
	ds_read_b128 v[202:205], v202
	ds_read_b128 v[206:209], v193
	s_waitcnt lgkmcnt(1)
	v_mfma_f32_16x16x32_bf16 v[60:63], v[194:197], v[202:205], v[60:63]
	v_mfma_f32_16x16x32_bf16 v[56:59], v[198:201], v[202:205], v[56:59]
	v_mfma_f32_16x16x32_bf16 v[52:55], v[214:217], v[202:205], v[52:55]
	v_mfma_f32_16x16x32_bf16 v[48:51], v[218:221], v[202:205], v[48:51]
	s_waitcnt lgkmcnt(0)
	v_mfma_f32_16x16x32_bf16 v[44:47], v[194:197], v[206:209], v[44:47]
	v_mfma_f32_16x16x32_bf16 v[40:43], v[198:201], v[206:209], v[40:43]
	v_mfma_f32_16x16x32_bf16 v[36:39], v[214:217], v[206:209], v[36:39]
	v_mfma_f32_16x16x32_bf16 v[32:35], v[218:221], v[206:209], v[32:35]
	s_cbranch_scc0 .LBB0_274
	s_waitcnt vmcnt(16)
	v_lshlrev_b32_e32 v196, 16, v158
	v_and_b32_e32 v158, 0xffff0000, v158
	v_lshlrev_b32_e32 v197, 16, v159
	v_and_b32_e32 v159, 0xffff0000, v159
	s_waitcnt vmcnt(14)
	v_lshlrev_b32_e32 v200, 16, v154
	v_and_b32_e32 v154, 0xffff0000, v154
	s_waitcnt vmcnt(13)
	v_lshlrev_b32_e32 v202, 16, v152
	v_and_b32_e32 v152, 0xffff0000, v152
	v_lshl_add_u64 v[194:195], v[114:115], 1, v[130:131]
	v_lshlrev_b32_e32 v198, 16, v156
	v_and_b32_e32 v156, 0xffff0000, v156
	v_lshlrev_b32_e32 v199, 16, v157
	v_and_b32_e32 v157, 0xffff0000, v157
	v_lshlrev_b32_e32 v201, 16, v155
	v_and_b32_e32 v155, 0xffff0000, v155
	v_lshlrev_b32_e32 v203, 16, v153
	v_and_b32_e32 v153, 0xffff0000, v153
	s_add_i32 s58, s58, 1
	s_cmp_eq_u32 s58, 8
	s_waitcnt vmcnt(0)
	v_add_f32_e32 v92, v92, v222
	v_add_f32_e32 v93, v93, v222
	v_add_f32_e32 v94, v94, v222
	v_add_f32_e32 v95, v95, v222
	v_add_f32_e32 v85, v85, v222
	v_add_f32_e32 v80, v80, v222
	v_add_f32_e32 v81, v81, v222
	v_add_f32_e32 v88, v88, v222
	v_add_f32_e32 v89, v89, v222
	v_add_f32_e32 v90, v90, v222
	v_add_f32_e32 v91, v91, v222
	v_mul_f32_e32 v92, v92, v196
	v_mul_f32_e32 v93, v93, v158
	v_mul_f32_e32 v94, v94, v197
	v_mul_f32_e32 v95, v95, v159
	v_mul_f32_e32 v85, v85, v154
	v_mul_f32_e32 v154, v80, v202
	v_mul_f32_e32 v152, v81, v152
	v_cvt_pk_bf16_f32 v80, v92, v93
	v_cvt_pk_bf16_f32 v81, v94, v95
	v_add_f32_e32 v84, v84, v222
	v_add_f32_e32 v86, v86, v222
	v_add_f32_e32 v87, v87, v222
	v_mul_f32_e32 v88, v88, v198
	v_mul_f32_e32 v89, v89, v156
	v_mul_f32_e32 v90, v90, v199
	v_mul_f32_e32 v91, v91, v157
	global_store_dwordx2 v[194:195], v[80:81], off
	v_cvt_pk_bf16_f32 v80, v88, v89
	v_cvt_pk_bf16_f32 v81, v90, v91
	v_add_f32_e32 v82, v82, v222
	v_add_f32_e32 v83, v83, v222
	v_mul_f32_e32 v84, v84, v200
	v_mul_f32_e32 v86, v86, v201
	v_mul_f32_e32 v87, v87, v155
	global_store_dwordx2 v[194:195], v[80:81], off offset:32
	v_cvt_pk_bf16_f32 v80, v84, v85
	v_cvt_pk_bf16_f32 v81, v86, v87
	v_mul_f32_e32 v82, v82, v203
	v_mul_f32_e32 v83, v83, v153
	global_store_dwordx2 v[194:195], v[80:81], off offset:64
	v_cvt_pk_bf16_f32 v80, v154, v152
	v_cvt_pk_bf16_f32 v81, v82, v83
	global_store_dwordx2 v[194:195], v[80:81], off offset:96
	v_lshlrev_b32_e32 v83, 16, v150
	v_and_b32_e32 v84, 0xffff0000, v150
	v_lshlrev_b32_e32 v85, 16, v151
	v_and_b32_e32 v86, 0xffff0000, v151
	v_lshlrev_b32_e32 v95, 16, v144
	v_and_b32_e32 v144, 0xffff0000, v144
	v_lshl_add_u64 v[80:81], v[116:117], 1, v[130:131]
	v_lshlrev_b32_e32 v87, 16, v148
	v_and_b32_e32 v88, 0xffff0000, v148
	v_lshlrev_b32_e32 v89, 16, v149
	v_and_b32_e32 v90, 0xffff0000, v149
	v_lshlrev_b32_e32 v91, 16, v146
	v_and_b32_e32 v92, 0xffff0000, v146
	v_lshlrev_b32_e32 v93, 16, v147
	v_and_b32_e32 v94, 0xffff0000, v147
	v_lshlrev_b32_e32 v146, 16, v145
	v_and_b32_e32 v145, 0xffff0000, v145
	v_add_f32_e32 v76, v76, v223
	v_add_f32_e32 v77, v77, v223
	v_add_f32_e32 v78, v78, v223
	v_add_f32_e32 v79, v79, v223
	v_add_f32_e32 v64, v64, v223
	v_add_f32_e32 v65, v65, v223
	v_add_f32_e32 v72, v72, v223
	v_add_f32_e32 v73, v73, v223
	v_add_f32_e32 v74, v74, v223
	v_add_f32_e32 v75, v75, v223
	v_add_f32_e32 v68, v68, v223
	v_add_f32_e32 v69, v69, v223
	v_add_f32_e32 v70, v70, v223
	v_add_f32_e32 v71, v71, v223
	v_add_f32_e32 v66, v66, v223
	v_add_f32_e32 v67, v67, v223
; __device__ __forceinline__ unsigned pk2(float lo, float hi) { return pg8::cvt_pk_bf16(lo, hi); }
; __device__ __forceinline__ float bflo(unsigned w) { return __uint_as_float(w << 16); }
; __device__ __forceinline__ float bfhi(unsigned w) { return __uint_as_float(w & 0xffff0000u); }
; __device__ __forceinline__ void sgu_phase(LAS unsigned char* lds, bf16* Z, const float* stats, const bf16* wsb, const float* lng, const float* lnb, const float* bs, int G, int c) {
;     ...
;             for (int m = 0; m < 4; ++m) { const int t = 64 * wr + 16 * m + fr; const float bsv = bs[g * 128 + t]; bf16* zr = Z + ((size_t)ck * 8 + g) * 32768 + t * 256 + 64 * wc + 4 * fq;
; #pragma unroll
;                 for (int n = 0; n < 4; ++n) { const v2u u2 = uu[m][n]; const f32x4 a = acc[m][n];
;                     *(v2u*)(zr + 16 * n) = (v2u){pk2(bflo(u2.x) * (a[0] + bsv), bfhi(u2.x) * (a[1] + bsv)), pk2(bflo(u2.y) * (a[2] + bsv), bfhi(u2.y) * (a[3] + bsv))}; } }
;             __syncthreads();
;         }
;     ...
;     }
	v_mul_f32_e32 v76, v76, v83
	v_mul_f32_e32 v77, v77, v84
	v_mul_f32_e32 v78, v78, v85
	v_mul_f32_e32 v79, v79, v86
	v_mul_f32_e32 v82, v64, v95
	v_mul_f32_e32 v83, v65, v144
	v_cvt_pk_bf16_f32 v64, v76, v77
	v_cvt_pk_bf16_f32 v65, v78, v79
	v_mul_f32_e32 v72, v72, v87
	v_mul_f32_e32 v73, v73, v88
	v_mul_f32_e32 v74, v74, v89
	v_mul_f32_e32 v75, v75, v90
	global_store_dwordx2 v[80:81], v[64:65], off
	v_cvt_pk_bf16_f32 v64, v72, v73
	v_cvt_pk_bf16_f32 v65, v74, v75
	v_mul_f32_e32 v68, v68, v91
	v_mul_f32_e32 v69, v69, v92
	v_mul_f32_e32 v70, v70, v93
	v_mul_f32_e32 v71, v71, v94
	global_store_dwordx2 v[80:81], v[64:65], off offset:32
	v_cvt_pk_bf16_f32 v64, v68, v69
	v_cvt_pk_bf16_f32 v65, v70, v71
	v_mul_f32_e32 v66, v66, v146
	v_mul_f32_e32 v67, v67, v145
	global_store_dwordx2 v[80:81], v[64:65], off offset:64
	v_cvt_pk_bf16_f32 v64, v82, v83
	v_cvt_pk_bf16_f32 v65, v66, v67
	global_store_dwordx2 v[80:81], v[64:65], off offset:96
	v_lshlrev_b32_e32 v67, 16, v142
	v_and_b32_e32 v68, 0xffff0000, v142
	v_lshlrev_b32_e32 v69, 16, v143
	v_and_b32_e32 v70, 0xffff0000, v143
	v_lshlrev_b32_e32 v79, 16, v136
	v_and_b32_e32 v80, 0xffff0000, v136
	v_lshl_add_u64 v[64:65], v[118:119], 1, v[130:131]
	v_lshlrev_b32_e32 v71, 16, v140
	v_and_b32_e32 v72, 0xffff0000, v140
	v_lshlrev_b32_e32 v73, 16, v141
	v_and_b32_e32 v74, 0xffff0000, v141
	v_lshlrev_b32_e32 v75, 16, v138
	v_and_b32_e32 v76, 0xffff0000, v138
	v_lshlrev_b32_e32 v77, 16, v139
	v_and_b32_e32 v78, 0xffff0000, v139
	v_lshlrev_b32_e32 v81, 16, v137
	v_and_b32_e32 v82, 0xffff0000, v137
	v_add_f32_e32 v60, v60, v224
	v_add_f32_e32 v61, v61, v224
	v_add_f32_e32 v62, v62, v224
	v_add_f32_e32 v63, v63, v224
	v_add_f32_e32 v48, v48, v224
	v_add_f32_e32 v49, v49, v224
	v_add_f32_e32 v56, v56, v224
	v_add_f32_e32 v57, v57, v224
	v_add_f32_e32 v58, v58, v224
	v_add_f32_e32 v59, v59, v224
	v_add_f32_e32 v52, v52, v224
	v_add_f32_e32 v53, v53, v224
	v_add_f32_e32 v54, v54, v224
	v_add_f32_e32 v55, v55, v224
	v_add_f32_e32 v50, v50, v224
	v_add_f32_e32 v51, v51, v224
	v_mul_f32_e32 v60, v60, v67
	v_mul_f32_e32 v61, v61, v68
	v_mul_f32_e32 v62, v62, v69
	v_mul_f32_e32 v63, v63, v70
	v_mul_f32_e32 v66, v48, v79
	v_mul_f32_e32 v67, v49, v80
	v_cvt_pk_bf16_f32 v48, v60, v61
	v_cvt_pk_bf16_f32 v49, v62, v63
	v_mul_f32_e32 v56, v56, v71
	v_mul_f32_e32 v57, v57, v72
	v_mul_f32_e32 v58, v58, v73
	v_mul_f32_e32 v59, v59, v74
	global_store_dwordx2 v[64:65], v[48:49], off
	v_cvt_pk_bf16_f32 v48, v56, v57
	v_cvt_pk_bf16_f32 v49, v58, v59
	v_mul_f32_e32 v52, v52, v75
	v_mul_f32_e32 v53, v53, v76
	v_mul_f32_e32 v54, v54, v77
	v_mul_f32_e32 v55, v55, v78
	global_store_dwordx2 v[64:65], v[48:49], off offset:32
	v_cvt_pk_bf16_f32 v48, v52, v53
	v_cvt_pk_bf16_f32 v49, v54, v55
	v_mul_f32_e32 v50, v50, v81
	v_mul_f32_e32 v51, v51, v82
	global_store_dwordx2 v[64:65], v[48:49], off offset:64
	v_cvt_pk_bf16_f32 v48, v66, v67
	v_cvt_pk_bf16_f32 v49, v50, v51
	global_store_dwordx2 v[64:65], v[48:49], off offset:96
	v_lshlrev_b32_e32 v51, 16, v134
	v_and_b32_e32 v52, 0xffff0000, v134
	v_lshlrev_b32_e32 v53, 16, v135
	v_and_b32_e32 v54, 0xffff0000, v135
	v_lshlrev_b32_e32 v63, 16, v126
	v_and_b32_e32 v64, 0xffff0000, v126
	v_lshl_add_u64 v[48:49], v[120:121], 1, v[130:131]
	v_lshlrev_b32_e32 v55, 16, v132
	v_and_b32_e32 v56, 0xffff0000, v132
	v_lshlrev_b32_e32 v57, 16, v133
	v_and_b32_e32 v58, 0xffff0000, v133
	v_lshlrev_b32_e32 v59, 16, v128
	v_and_b32_e32 v60, 0xffff0000, v128
	v_lshlrev_b32_e32 v61, 16, v129
	v_and_b32_e32 v62, 0xffff0000, v129
	v_lshlrev_b32_e32 v65, 16, v127
	v_and_b32_e32 v66, 0xffff0000, v127
	v_add_f32_e32 v44, v44, v225
	v_add_f32_e32 v45, v45, v225
	v_add_f32_e32 v46, v46, v225
	v_add_f32_e32 v47, v47, v225
	v_add_f32_e32 v32, v32, v225
	v_add_f32_e32 v33, v33, v225
	v_add_f32_e32 v40, v40, v225
	v_add_f32_e32 v41, v41, v225
	v_add_f32_e32 v42, v42, v225
	v_add_f32_e32 v43, v43, v225
	v_add_f32_e32 v36, v36, v225
	v_add_f32_e32 v37, v37, v225
	v_add_f32_e32 v38, v38, v225
	v_add_f32_e32 v39, v39, v225
	v_add_f32_e32 v34, v34, v225
	v_add_f32_e32 v35, v35, v225
	v_mul_f32_e32 v44, v44, v51
	v_mul_f32_e32 v45, v45, v52
	v_mul_f32_e32 v46, v46, v53
	v_mul_f32_e32 v47, v47, v54
	v_mul_f32_e32 v50, v32, v63
	v_mul_f32_e32 v51, v33, v64
	v_cvt_pk_bf16_f32 v32, v44, v45
	v_cvt_pk_bf16_f32 v33, v46, v47
	v_mul_f32_e32 v40, v40, v55
	v_mul_f32_e32 v41, v41, v56
	v_mul_f32_e32 v42, v42, v57
	v_mul_f32_e32 v43, v43, v58
	global_store_dwordx2 v[48:49], v[32:33], off
	v_cvt_pk_bf16_f32 v32, v40, v41
	v_cvt_pk_bf16_f32 v33, v42, v43
	v_mul_f32_e32 v36, v36, v59
	v_mul_f32_e32 v37, v37, v60
	v_mul_f32_e32 v38, v38, v61
	v_mul_f32_e32 v39, v39, v62
	global_store_dwordx2 v[48:49], v[32:33], off offset:32
	v_cvt_pk_bf16_f32 v32, v36, v37
	v_cvt_pk_bf16_f32 v33, v38, v39
	v_mul_f32_e32 v34, v34, v65
	v_mul_f32_e32 v35, v35, v66
	global_store_dwordx2 v[48:49], v[32:33], off offset:64
	v_cvt_pk_bf16_f32 v32, v50, v51
	v_cvt_pk_bf16_f32 v33, v34, v35
	global_store_dwordx2 v[48:49], v[32:33], off offset:96
	s_barrier
	s_cbranch_scc0 .LBB0_271
	s_add_i32 s10, s10, s0
	s_cmpk_gt_i32 s10, 0xff
	s_cbranch_scc0 .LBB0_268
